# v13 + K tile LDS swizzle widened to (row&15)<<4 so the ds_read_b128 K fragment reads are bank-conflict free (was 2-way)
# speedup vs baseline: 1.0017x; 1.0017x over previous
.LBB0_657:
	s_ashr_i32 s25, s24, 31
	s_mul_i32 s27, s24, 0x600
	s_mul_hi_i32 s7, s24, 0x600
	s_add_u32 s0, s42, s27
	s_addc_u32 s1, s43, s7
	s_lshl_b32 s6, s6, 6
	s_and_b32 s6, s6, 0x100
	s_add_u32 s0, s0, s6
	s_addc_u32 s1, s1, 0
	v_ashrrev_i32_e32 v48, 4, v50
	s_add_u32 s27, s44, s27
	v_lshlrev_b32_e32 v16, 3, v50
	v_add_u32_e32 v17, 32, v48
	s_movk_i32 s38, 0x300
	s_addc_u32 s7, s45, s7
	v_and_b32_e32 v51, 0x78, v16
	v_mad_i64_i32 v[0:1], s[36:37], v48, s38, 0
	v_mad_i64_i32 v[2:3], s[36:37], v17, s38, 0
	s_add_u32 s6, s27, s6
	v_or_b32_e32 v0, v0, v51
	v_or_b32_e32 v2, v2, v51
	s_addc_u32 s7, s7, 0
	v_lshlrev_b64 v[8:9], 1, v[0:1]
	v_lshlrev_b64 v[10:11], 1, v[2:3]
	v_lshl_add_u64 v[0:1], s[6:7], 0, v[8:9]
	v_lshl_add_u64 v[4:5], s[6:7], 0, v[10:11]
	v_lshl_add_u64 v[8:9], s[0:1], 0, v[8:9]
	v_lshl_add_u64 v[12:13], s[0:1], 0, v[10:11]
	global_load_dwordx4 v[0:3], v[0:1], off
	s_nop 0
	global_load_dwordx4 v[4:7], v[4:5], off
	s_nop 0
	global_load_dwordx4 v[8:11], v[8:9], off
	s_nop 0
	global_load_dwordx4 v[12:15], v[12:13], off
	v_lshlrev_b32_e32 v19, 4, v199
	v_and_b32_e32 v20, 0xfffff0, v48
	v_lshlrev_b32_e32 v21, 1, v48
	v_lshrrev_b32_e32 v22, 1, v48
	v_and_b32_e32 v23, 3, v48
	v_and_b32_e32 v69, 0xf0, v19
	v_and_or_b32 v19, v21, 8, v20
	v_and_or_b32 v20, v22, 4, v23
	v_and_b32_e32 v22, 0xfffff0, v17
	v_lshlrev_b32_e32 v23, 1, v17
	v_and_b32_e32 v18, 0xf0, v50
	v_bfe_u32 v16, v16, 5, 2
	v_lshlrev_b32_e32 v24, 8, v48
	v_lshlrev_b32_e32 v21, 1, v51
	v_lshlrev_b32_e32 v17, 8, v17
	v_lshrrev_b32_e32 v19, 1, v19
	v_and_or_b32 v22, v23, 8, v22
	v_bitop3_b32 v23, v21, v24, v18 bitop3:0xde
	v_bitop3_b32 v17, v21, v17, v18 bitop3:0xde
	v_or_b32_e32 v18, v19, v16
	v_lshrrev_b32_e32 v19, 1, v22
	v_lshlrev_b32_e32 v68, 8, v199
	v_lshlrev_b32_e32 v20, 6, v20
	v_and_b32_e32 v26, 48, v21
	v_add_u32_e32 v206, 0x100, v17
	v_lshlrev_b32_e32 v17, 9, v18
	v_or_b32_e32 v16, v19, v16
	v_bitop3_b32 v25, v178, v68, v69 bitop3:0xde
	v_or3_b32 v17, v17, v20, v26
	v_lshlrev_b32_e32 v16, 9, v16
	v_add_u32_e32 v204, 0x100, v25
	v_or3_b32 v16, v16, v20, v26
	v_add_u32_e32 v207, 0x100, v17
	v_add_u32_e32 v205, 0x100, v23
	v_add_u32_e32 v208, 0x100, v16
	s_waitcnt vmcnt(0)
	v_and_b32_e32 v76, 63, v50
	s_add_i32 s27, s93, 0x100
	v_add_u32_e32 v72, 0xa0, v48
	v_mad_i64_i32 v[72:73], s[36:37], v72, s38, 0
	v_or_b32_e32 v72, v72, v51
	v_lshlrev_b64 v[72:73], 1, v[72:73]
	v_lshl_add_u64 v[74:75], s[6:7], 0, v[72:73]
	s_cmp_lg_u32 0x100, -1
	s_mov_b32 s49, s48
	s_mov_b32 s50, s48
	s_mov_b32 s51, s48
	s_mov_b32 s52, s48
	s_mov_b32 s53, s48
	s_mov_b32 s54, s48
	s_mov_b32 s55, s48
	s_mov_b32 s56, s48
	s_mov_b32 s57, s48
	s_mov_b32 s58, s48
	s_mov_b32 s59, s48
	s_mov_b32 s60, s48
	s_mov_b32 s61, s48
	s_mov_b32 s62, s48
	s_waitcnt vmcnt(3)
	ds_write_b128 v207, v[0:3]
	s_waitcnt vmcnt(2)
	ds_write_b128 v208, v[4:7]
	s_waitcnt vmcnt(1)
	ds_write_b128 v205, v[8:11] offset:32768
	s_waitcnt vmcnt(0)
	ds_write_b128 v206, v[12:15] offset:32768
	s_waitcnt lgkmcnt(0)
	s_barrier
	ds_read_b128 v[0:3], v204 offset:32768
	ds_read_b128 v[4:7], v204 offset:40960
	s_waitcnt lgkmcnt(1)
	v_mfma_f32_32x32x16_bf16 v[16:31], v[0:3], v[96:99], 0
	v_or_b32_e32 v0, 32, v178
	v_bitop3_b32 v0, v0, v68, v69 bitop3:0xde
	v_add_u32_e32 v209, 0x100, v0
	v_or_b32_e32 v8, 0xa0, v178
	v_or_b32_e32 v9, 0xc0, v178
	v_bitop3_b32 v52, v9, v68, v69 bitop3:0xde
	v_add_u32_e32 v228, 0x100, v52
	s_waitcnt lgkmcnt(0)
	v_mfma_f32_32x32x16_bf16 v[32:47], v[4:7], v[96:99], 0
	ds_read_b128 v[0:3], v209 offset:32768
	ds_read_b128 v[4:7], v209 offset:40960
	v_lshlrev_b32_e32 v10, 4, v76
	v_lshlrev_b32_e32 v11, 1, v76
	v_add_u32_e32 v14, 64, v48
	v_add_u32_e32 v15, 0x60, v48
	v_and_b32_e32 v49, 0xc0, v10
	v_and_b32_e32 v70, 32, v11
	s_waitcnt lgkmcnt(1)
	v_mfma_f32_32x32x16_bf16 v[16:31], v[0:3], v[100:103], v[16:31]
	v_or_b32_e32 v0, 64, v178
	v_bitop3_b32 v0, v0, v68, v69 bitop3:0xde
	v_add_u32_e32 v226, 0x100, v0
	v_mad_i64_i32 v[10:11], s[36:37], v15, s38, 0
	v_or_b32_e32 v10, v10, v51
	v_and_b32_e32 v12, 0x3fffffc0, v50
	s_waitcnt lgkmcnt(0)
	v_mfma_f32_32x32x16_bf16 v[32:47], v[4:7], v[100:103], v[32:47]
	ds_read_b128 v[0:3], v226 offset:32768
	ds_read_b128 v[4:7], v226 offset:40960
	v_lshlrev_b32_e32 v13, 3, v76
	v_and_b32_e32 v71, 0x100, v13
	v_lshl_add_u32 v187, v12, 2, s27
	s_cselect_b32 s27, 0x100, 0
	s_mov_b32 s63, s48
	s_mov_b32 s35, 1
	s_waitcnt lgkmcnt(1)
	v_mfma_f32_32x32x16_bf16 v[16:31], v[0:3], v[104:107], v[16:31]
	v_or_b32_e32 v0, 0x60, v178
	v_bitop3_b32 v0, v0, v68, v69 bitop3:0xde
	v_add_u32_e32 v225, 0x100, v0
	ds_read_b128 v[0:3], v225 offset:32768
	v_lshl_add_u32 v200, v199, 2, v187
	v_mov_b32_e32 v201, 0
	s_waitcnt lgkmcnt(1)
	v_mfma_f32_32x32x16_bf16 v[32:47], v[4:7], v[104:107], v[32:47]
	ds_read_b128 v[4:7], v225 offset:40960
	s_waitcnt lgkmcnt(1)
	v_mfma_f32_32x32x16_bf16 v[16:31], v[0:3], v[108:111], v[16:31]
	v_or_b32_e32 v0, 0x80, v178
	v_bitop3_b32 v0, v0, v68, v69 bitop3:0xde
	v_add_u32_e32 v227, 0x100, v0
	ds_read_b128 v[0:3], v227 offset:32768
	s_waitcnt lgkmcnt(1)
	v_mfma_f32_32x32x16_bf16 v[32:47], v[4:7], v[108:111], v[32:47]
	ds_read_b128 v[4:7], v227 offset:40960
	s_waitcnt lgkmcnt(1)
	v_mfma_f32_32x32x16_bf16 v[16:31], v[0:3], v[112:115], v[16:31]
	v_bitop3_b32 v0, v8, v68, v69 bitop3:0xde
	v_add_u32_e32 v229, 0x100, v0
	ds_read_b128 v[0:3], v229 offset:32768
	v_mad_i64_i32 v[8:9], s[36:37], v14, s38, 0
	v_or_b32_e32 v8, v8, v51
	v_lshlrev_b64 v[8:9], 1, v[8:9]
	s_waitcnt lgkmcnt(1)
	v_mfma_f32_32x32x16_bf16 v[32:47], v[4:7], v[112:115], v[32:47]
	ds_read_b128 v[4:7], v229 offset:40960
	v_and_or_b32 v14, v13, 24, v49
	v_lshl_add_u64 v[12:13], s[6:7], 0, v[8:9]
	v_or3_b32 v77, v14, v70, v71
	v_ashrrev_i32_e32 v49, 31, v48
	v_add_u32_e32 v203, s27, v77
	s_waitcnt lgkmcnt(1)
	v_mfma_f32_32x32x16_bf16 v[16:31], v[0:3], v[116:119], v[16:31]
	ds_read_b128 v[0:3], v228 offset:32768
	s_waitcnt lgkmcnt(1)
	v_mfma_f32_32x32x16_bf16 v[32:47], v[4:7], v[116:119], v[32:47]
	v_lshlrev_b64 v[4:5], 1, v[10:11]
	v_lshl_add_u64 v[6:7], s[6:7], 0, v[4:5]
	global_load_dwordx4 v[52:55], v[12:13], off
	global_load_dwordx4 v[56:59], v[6:7], off
	v_lshl_add_u64 v[6:7], s[0:1], 0, v[8:9]
	v_lshl_add_u64 v[4:5], s[0:1], 0, v[4:5]
	global_load_dwordx4 v[60:63], v[6:7], off
	global_load_dwordx4 v[64:67], v[4:5], off
	ds_read_b128 v[4:7], v228 offset:40960
	s_waitcnt lgkmcnt(1)
	v_mfma_f32_32x32x16_bf16 v[16:31], v[0:3], v[120:123], v[16:31]
	v_or_b32_e32 v0, 0xe0, v178
	v_bitop3_b32 v0, v0, v68, v69 bitop3:0xde
	v_add_u32_e32 v230, 0x100, v0
	ds_read_b128 v[0:3], v230 offset:32768
	ds_read_b128 v[68:71], v230 offset:40960
	s_waitcnt lgkmcnt(2)
	v_mfma_f32_32x32x16_bf16 v[32:47], v[4:7], v[120:123], v[32:47]
	s_waitcnt lgkmcnt(1)
	v_mfma_f32_32x32x16_bf16 v[16:31], v[0:3], v[124:127], v[16:31]
	v_mov_b64_e32 v[0:1], s[48:49]
	v_mov_b64_e32 v[14:15], s[62:63]
	v_mov_b64_e32 v[2:3], s[50:51]
	v_mov_b64_e32 v[4:5], s[52:53]
	v_mov_b64_e32 v[6:7], s[54:55]
	v_mov_b64_e32 v[8:9], s[56:57]
	v_mov_b64_e32 v[10:11], s[58:59]
	s_waitcnt lgkmcnt(0)
	v_mfma_f32_32x32x16_bf16 v[32:47], v[68:71], v[124:127], v[32:47]
	s_nop 2
	v_max_f32_e32 v68, v17, v17
	v_max_f32_e32 v69, v16, v16
	v_max_f32_e32 v68, v69, v68
	v_max3_f32 v68, v68, v18, v19
	v_max3_f32 v68, v68, v20, v21
	v_max3_f32 v68, v68, v22, v23
	v_max3_f32 v68, v68, v24, v25
	v_max3_f32 v68, v68, v26, v27
	v_max3_f32 v68, v68, v28, v29
	v_max3_f32 v68, v68, v30, v31
	v_max3_f32 v68, v68, v32, v33
	v_max3_f32 v68, v68, v34, v35
	v_max3_f32 v68, v68, v36, v37
	v_max3_f32 v68, v68, v38, v39
	v_max3_f32 v68, v68, v40, v41
	v_max3_f32 v68, v68, v42, v43
	v_max3_f32 v68, v68, v44, v45
	v_max3_f32 v78, v68, v46, v47
	v_mov_b32_e32 v68, v78
	s_nop 1
	v_permlane32_swap_b32_e32 v78, v68
	v_max_f32_e32 v79, v68, v68
	v_add_u32_e32 v68, 0x80, v48
	v_mad_i64_i32 v[68:69], s[36:37], v68, s38, 0
	v_or_b32_e32 v68, v68, v51
	v_lshlrev_b64 v[68:69], 1, v[68:69]
	v_lshl_add_u64 v[70:71], s[6:7], 0, v[68:69]
	v_lshl_add_u64 v[68:69], s[0:1], 0, v[68:69]
	global_load_dwordx4 v[128:131], v[70:71], off
	global_load_dwordx4 v[136:139], v[74:75], off
	v_lshl_add_u64 v[70:71], s[0:1], 0, v[72:73]
	global_load_dwordx4 v[132:135], v[68:69], off
	global_load_dwordx4 v[140:143], v[70:71], off
	v_max_f32_e32 v51, v78, v78
	v_max_f32_e32 v51, v51, v79
	v_add_f32_e32 v68, 0x7149f2ca, v51
	v_max_f32_e32 v51, 0xf149f2ca, v51
	s_waitcnt vmcnt(4)
	s_waitcnt vmcnt(7)
	ds_write_b128 v207, v[52:55] offset:16384
	s_waitcnt vmcnt(6)
	ds_write_b128 v208, v[56:59] offset:16384
	s_waitcnt vmcnt(5)
	ds_write_b128 v205, v[60:63] offset:49152
	s_waitcnt vmcnt(4)
	ds_write_b128 v206, v[64:67] offset:49152
	v_sub_f32_e32 v52, 0xf149f2ca, v51
	v_mul_f32_e32 v52, 0x3e0293ee, v52
	v_cmp_ge_f32_e32 vcc, s69, v68
	v_exp_f32_e32 v52, v52
	s_cmp_eq_u64 vcc, exec
	s_cselect_b64 vcc, -1, 0
	v_cndmask_b32_e32 v164, v51, v222, vcc
	v_cndmask_b32_e64 v231, v52, 1.0, vcc
	v_mul_f32_e32 v52, 0xbe0293ee, v164
	v_fmamk_f32 v16, v16, 0x3e0293ee, v52
	v_exp_f32_e32 v161, v16
	v_fmamk_f32 v16, v17, 0x3e0293ee, v52
	v_exp_f32_e32 v175, v16
	v_fmamk_f32 v16, v18, 0x3e0293ee, v52
	v_exp_f32_e32 v162, v16
	v_fmamk_f32 v16, v19, 0x3e0293ee, v52
	v_exp_f32_e32 v235, v16
	v_fmamk_f32 v16, v20, 0x3e0293ee, v52
	v_exp_f32_e32 v174, v16
	v_fmamk_f32 v16, v21, 0x3e0293ee, v52
	v_exp_f32_e32 v238, v16
	v_fmamk_f32 v16, v22, 0x3e0293ee, v52
	v_exp_f32_e32 v163, v16
	v_fmamk_f32 v16, v23, 0x3e0293ee, v52
	v_exp_f32_e32 v173, v16
	v_fmamk_f32 v16, v24, 0x3e0293ee, v52
	v_exp_f32_e32 v169, v16
	v_fmamk_f32 v16, v25, 0x3e0293ee, v52
	v_exp_f32_e32 v171, v16
	v_fmamk_f32 v16, v26, 0x3e0293ee, v52
	v_exp_f32_e32 v170, v16
	v_fmamk_f32 v16, v27, 0x3e0293ee, v52
	v_exp_f32_e32 v172, v16
	v_fmamk_f32 v16, v28, 0x3e0293ee, v52
	v_exp_f32_e32 v165, v16
	v_fmamk_f32 v16, v29, 0x3e0293ee, v52
	v_exp_f32_e32 v167, v16
	v_fmamk_f32 v16, v30, 0x3e0293ee, v52
	v_exp_f32_e32 v166, v16
	v_lshl_add_u64 v[16:17], s[24:25], 0, v[48:49]
	v_mad_u64_u32 v[18:19], s[0:1], v16, s90, 0
	v_pk_fma_f32 v[144:145], v[46:47], s[64:65], v[52:53] op_sel_hi:[1,0,0]
	v_pk_fma_f32 v[150:151], v[44:45], s[64:65], v[52:53] op_sel_hi:[1,0,0]
	v_pk_fma_f32 v[154:155], v[42:43], s[64:65], v[52:53] op_sel_hi:[1,0,0]
	v_pk_fma_f32 v[146:147], v[40:41], s[64:65], v[52:53] op_sel_hi:[1,0,0]
	v_pk_fma_f32 v[148:149], v[38:39], s[64:65], v[52:53] op_sel_hi:[1,0,0]
	v_pk_fma_f32 v[152:153], v[36:37], s[64:65], v[52:53] op_sel_hi:[1,0,0]
	v_pk_fma_f32 v[156:157], v[34:35], s[64:65], v[52:53] op_sel_hi:[1,0,0]
	v_pk_fma_f32 v[158:159], v[32:33], s[64:65], v[52:53] op_sel_hi:[1,0,0]
	v_fmac_f32_e32 v52, 0x3e0293ee, v31
	s_and_b32 s0, s26, 4
	v_and_b32_e32 v16, 15, v50
	v_exp_f32_e32 v168, v52
	s_lshl_b32 s0, s0, 6
	v_lshlrev_b32_e32 v16, 4, v16
	v_mad_i32_i24 v17, v17, s90, v19
	v_or3_b32 v16, v18, s0, v16
	v_mov_b64_e32 v[12:13], s[60:61]
	s_addk_i32 s27, 0x4000
	v_lshl_add_u64 v[188:189], s[10:11], 0, v[16:17]
	v_mov_b64_e32 v[62:63], v[14:15]
	v_mov_b64_e32 v[46:47], v[14:15]
	v_mov_b64_e32 v[30:31], v[14:15]
	v_cmp_gt_u32_e64 s[6:7], 32, v76
	v_add_u32_e32 v202, s27, v77
	v_mov_b64_e32 v[60:61], v[12:13]
	v_mov_b64_e32 v[58:59], v[10:11]
	v_mov_b64_e32 v[56:57], v[8:9]
	v_mov_b64_e32 v[54:55], v[6:7]
	v_mov_b64_e32 v[52:53], v[4:5]
	v_mov_b64_e32 v[50:51], v[2:3]
	v_mov_b64_e32 v[48:49], v[0:1]
	v_mov_b64_e32 v[44:45], v[12:13]
	v_mov_b64_e32 v[42:43], v[10:11]
	v_mov_b64_e32 v[40:41], v[8:9]
	v_mov_b64_e32 v[38:39], v[6:7]
	v_mov_b64_e32 v[36:37], v[4:5]
	v_mov_b64_e32 v[34:35], v[2:3]
	v_mov_b64_e32 v[32:33], v[0:1]
	v_mov_b64_e32 v[28:29], v[12:13]
	v_mov_b64_e32 v[26:27], v[10:11]
	v_mov_b64_e32 v[24:25], v[8:9]
	v_mov_b64_e32 v[22:23], v[6:7]
	v_mov_b64_e32 v[20:21], v[4:5]
	v_mov_b64_e32 v[18:19], v[2:3]
	v_mov_b64_e32 v[16:17], v[0:1]
	s_waitcnt lgkmcnt(0)
	s_barrier

.LBB0_682:
	s_and_b64 s[0:1], s[18:19], exec
	s_cselect_b32 s22, s83, s79
	s_ashr_i32 s23, s22, 31
	s_mul_i32 s1, s22, 0x600
	s_mul_hi_i32 s0, s22, 0x600
	s_add_u32 s6, s42, s1
	s_addc_u32 s7, s43, s0
	s_add_u32 s24, s6, s88
	s_addc_u32 s25, s7, 0
	s_add_u32 s1, s44, s1
	s_addc_u32 s0, s45, s0
	v_ashrrev_i32_e32 v48, 4, v50
	s_add_u32 s26, s1, s88
	v_lshlrev_b32_e32 v16, 3, v50
	v_add_u32_e32 v17, 32, v48
	s_movk_i32 s6, 0x300
	s_addc_u32 s27, s0, 0
	v_and_b32_e32 v51, 0x78, v16
	s_waitcnt vmcnt(3)
	v_mad_i64_i32 v[0:1], s[0:1], v48, s6, 0
	v_mad_i64_i32 v[2:3], s[0:1], v17, s6, 0
	v_or_b32_e32 v0, v0, v51
	v_or_b32_e32 v2, v2, v51
	s_waitcnt vmcnt(1)
	v_lshlrev_b64 v[8:9], 1, v[0:1]
	v_lshlrev_b64 v[10:11], 1, v[2:3]
	v_lshl_add_u64 v[0:1], s[26:27], 0, v[8:9]
	v_lshl_add_u64 v[4:5], s[26:27], 0, v[10:11]
	v_lshl_add_u64 v[8:9], s[24:25], 0, v[8:9]
	s_waitcnt vmcnt(0)
	v_lshl_add_u64 v[12:13], s[24:25], 0, v[10:11]
	global_load_dwordx4 v[0:3], v[0:1], off offset:512
	s_nop 0
	global_load_dwordx4 v[4:7], v[4:5], off offset:512
	s_nop 0
	global_load_dwordx4 v[8:11], v[8:9], off offset:512
	s_nop 0
	global_load_dwordx4 v[12:15], v[12:13], off offset:512
	v_lshlrev_b32_e32 v19, 4, v165
	v_and_b32_e32 v20, 0xfffff0, v48
	v_lshlrev_b32_e32 v21, 1, v48
	v_lshrrev_b32_e32 v22, 1, v48
	v_and_b32_e32 v23, 3, v48
	v_and_b32_e32 v69, 0xf0, v19
	v_and_or_b32 v19, v21, 8, v20
	v_and_or_b32 v20, v22, 4, v23
	v_and_b32_e32 v22, 0xfffff0, v17
	v_lshlrev_b32_e32 v23, 1, v17
	v_and_b32_e32 v18, 0xf0, v50
	v_bfe_u32 v16, v16, 5, 2
	v_lshlrev_b32_e32 v24, 8, v48
	v_lshlrev_b32_e32 v21, 1, v51
	v_lshlrev_b32_e32 v17, 8, v17
	v_lshrrev_b32_e32 v19, 1, v19
	v_and_or_b32 v22, v23, 8, v22
	v_bitop3_b32 v23, v21, v24, v18 bitop3:0xde
	v_bitop3_b32 v17, v21, v17, v18 bitop3:0xde
	v_or_b32_e32 v18, v19, v16
	v_lshrrev_b32_e32 v19, 1, v22
	v_lshlrev_b32_e32 v68, 8, v165
	v_lshlrev_b32_e32 v20, 6, v20
	v_and_b32_e32 v26, 48, v21
	v_add_u32_e32 v172, 0x100, v17
	v_lshlrev_b32_e32 v17, 9, v18
	v_or_b32_e32 v16, v19, v16
	v_bitop3_b32 v25, v178, v68, v69 bitop3:0xde
	v_or3_b32 v17, v17, v20, v26
	v_lshlrev_b32_e32 v16, 9, v16
	v_add_u32_e32 v170, 0x100, v25
	v_or3_b32 v16, v16, v20, v26
	v_add_u32_e32 v173, 0x100, v17
	v_add_u32_e32 v171, 0x100, v23
	v_add_u32_e32 v174, 0x100, v16
	s_waitcnt vmcnt(0)
	v_and_b32_e32 v76, 63, v50
	s_add_i32 s90, s36, 0x100
	v_add_u32_e32 v72, 0xa0, v48
	v_mad_i64_i32 v[72:73], s[0:1], v72, s6, 0
	v_or_b32_e32 v72, v72, v51
	v_lshlrev_b64 v[72:73], 1, v[72:73]
	v_lshl_add_u64 v[74:75], s[26:27], 0, v[72:73]
	s_mov_b32 s49, s48
	s_mov_b32 s50, s48
	s_mov_b32 s51, s48
	s_mov_b32 s52, s48
	s_mov_b32 s53, s48
	s_mov_b32 s54, s48
	s_mov_b32 s55, s48
	s_mov_b32 s56, s48
	s_mov_b32 s57, s48
	s_mov_b32 s58, s48
	s_mov_b32 s59, s48
	s_mov_b32 s60, s48
	s_mov_b32 s61, s48
	s_mov_b32 s62, s48
	s_mov_b32 s63, s48
	s_cmp_lg_u32 0x100, -1
	s_cselect_b32 s36, 0x100, 0
	s_lshr_b32 s89, s28, 6
	s_waitcnt vmcnt(3)
	ds_write_b128 v173, v[0:3]
	s_waitcnt vmcnt(2)
	ds_write_b128 v174, v[4:7]
	s_waitcnt vmcnt(1)
	ds_write_b128 v171, v[8:11] offset:32768
	s_waitcnt vmcnt(0)
	ds_write_b128 v172, v[12:15] offset:32768
	s_waitcnt lgkmcnt(0)
	s_barrier
	ds_read_b128 v[0:3], v170 offset:32768
	ds_read_b128 v[4:7], v170 offset:40960
	v_or_b32_e32 v8, 32, v178
	s_waitcnt lgkmcnt(1)
	v_mfma_f32_32x32x16_bf16 v[16:31], v[0:3], v[100:103], 0
	v_lshlrev_b32_e32 v0, 1, v76
	v_and_b32_e32 v14, 32, v0
	v_bitop3_b32 v0, v8, v68, v69 bitop3:0xde
	v_add_u32_e32 v186, 0x100, v0
	ds_read_b128 v[0:3], v186 offset:32768
	v_or_b32_e32 v9, 64, v178
	v_add_u32_e32 v13, 64, v48
	s_waitcnt lgkmcnt(1)
	v_mfma_f32_32x32x16_bf16 v[32:47], v[4:7], v[100:103], 0
	v_bitop3_b32 v4, v9, v68, v69 bitop3:0xde
	v_add_u32_e32 v175, 0x100, v4
	ds_read_b128 v[4:7], v186 offset:40960
	v_lshlrev_b32_e32 v12, 4, v76
	v_mad_i64_i32 v[8:9], s[0:1], v13, s6, 0
	v_lshlrev_b32_e32 v11, 3, v76
	s_waitcnt lgkmcnt(1)
	v_mfma_f32_32x32x16_bf16 v[16:31], v[0:3], v[108:111], v[16:31]
	ds_read_b128 v[0:3], v175 offset:32768
	v_and_b32_e32 v12, 0xc0, v12
	v_or_b32_e32 v8, v8, v51
	v_and_b32_e32 v10, 0x3fffffc0, v50
	v_and_b32_e32 v15, 0x100, v11
	v_and_or_b32 v11, v11, 24, v12
	v_lshlrev_b64 v[8:9], 1, v[8:9]
	s_waitcnt lgkmcnt(1)
	v_mfma_f32_32x32x16_bf16 v[32:47], v[4:7], v[108:111], v[32:47]
	v_add_u32_e32 v4, 0x60, v48
	v_mad_i64_i32 v[4:5], s[0:1], v4, s6, 0
	v_or_b32_e32 v4, v4, v51
	v_lshlrev_b64 v[4:5], 1, v[4:5]
	v_or3_b32 v77, v11, v14, v15
	v_lshl_add_u32 v161, v10, 2, s90
	s_waitcnt lgkmcnt(0)
	v_mfma_f32_32x32x16_bf16 v[16:31], v[0:3], v[96:99], v[16:31]
	v_or_b32_e32 v0, 0x60, v178
	v_lshl_add_u64 v[10:11], s[26:27], 0, v[8:9]
	v_lshl_add_u64 v[6:7], s[26:27], 0, v[4:5]
	v_bitop3_b32 v0, v0, v68, v69 bitop3:0xde
	global_load_dwordx4 v[52:55], v[10:11], off offset:512
	global_load_dwordx4 v[56:59], v[6:7], off offset:512
	v_lshl_add_u64 v[6:7], s[24:25], 0, v[8:9]
	v_lshl_add_u64 v[4:5], s[24:25], 0, v[4:5]
	v_add_u32_e32 v187, 0x100, v0
	global_load_dwordx4 v[60:63], v[6:7], off offset:512
	global_load_dwordx4 v[64:67], v[4:5], off offset:512
	ds_read_b128 v[4:7], v175 offset:40960
	ds_read_b128 v[0:3], v187 offset:32768
	ds_read_b128 v[68:71], v187 offset:40960
	s_waitcnt lgkmcnt(2)
	v_mfma_f32_32x32x16_bf16 v[32:47], v[4:7], v[96:99], v[32:47]
	v_add_u32_e32 v169, s36, v77
	v_ashrrev_i32_e32 v49, 31, v48
	s_mov_b32 s37, s48
	s_movk_i32 s28, 0x600
	s_mov_b32 s91, 1
	v_lshl_add_u32 v166, v165, 2, v161
	v_mov_b32_e32 v167, 0
	s_waitcnt lgkmcnt(1)
	v_mfma_f32_32x32x16_bf16 v[16:31], v[0:3], v[104:107], v[16:31]
	v_mov_b64_e32 v[0:1], s[48:49]
	v_mov_b64_e32 v[2:3], s[50:51]
	v_mov_b64_e32 v[4:5], s[52:53]
	v_mov_b64_e32 v[6:7], s[54:55]
	v_mov_b64_e32 v[8:9], s[56:57]
	v_mov_b64_e32 v[10:11], s[58:59]
	v_mov_b64_e32 v[12:13], s[60:61]
	s_waitcnt lgkmcnt(0)
	v_mfma_f32_32x32x16_bf16 v[32:47], v[68:71], v[104:107], v[32:47]
	s_nop 2
	v_max_f32_e32 v68, v17, v17
	v_max_f32_e32 v69, v16, v16
	v_max_f32_e32 v68, v69, v68
	v_max3_f32 v68, v68, v18, v19
	v_max3_f32 v68, v68, v20, v21
	v_max3_f32 v68, v68, v22, v23
	v_max3_f32 v68, v68, v24, v25
	v_max3_f32 v68, v68, v26, v27
	v_max3_f32 v68, v68, v28, v29
	v_max3_f32 v68, v68, v30, v31
	v_max3_f32 v68, v68, v32, v33
	v_max3_f32 v68, v68, v34, v35
	v_max3_f32 v68, v68, v36, v37
	v_max3_f32 v68, v68, v38, v39
	v_max3_f32 v68, v68, v40, v41
	v_max3_f32 v68, v68, v42, v43
	v_max3_f32 v68, v68, v44, v45
	v_max3_f32 v68, v68, v46, v47
	v_mov_b32_e32 v69, v68
	s_nop 1
	v_permlane32_swap_b32_e32 v68, v69
	v_max_f32_e32 v69, v69, v69
	v_max_f32_e32 v68, v68, v68
	v_max_f32_e32 v78, v68, v69
	v_add_u32_e32 v68, 0x80, v48
	v_mad_i64_i32 v[68:69], s[0:1], v68, s6, 0
	v_or_b32_e32 v68, v68, v51
	v_lshlrev_b64 v[68:69], 1, v[68:69]
	v_lshl_add_u64 v[70:71], s[26:27], 0, v[68:69]
	v_lshl_add_u64 v[68:69], s[24:25], 0, v[68:69]
	global_load_dwordx4 v[112:115], v[70:71], off offset:512
	global_load_dwordx4 v[120:123], v[74:75], off offset:512
	v_lshl_add_u64 v[70:71], s[24:25], 0, v[72:73]
	global_load_dwordx4 v[116:119], v[68:69], off offset:512
	global_load_dwordx4 v[124:127], v[70:71], off offset:512
	v_mov_b64_e32 v[14:15], s[62:63]
	v_add_f32_e32 v51, 0x7149f2ca, v78
	s_mov_b32 s49, 0x42800000
	v_cmp_ge_f32_e32 vcc, s49, v51
	v_max_f32_e32 v51, 0xf149f2ca, v78
	s_waitcnt vmcnt(4)
	s_waitcnt vmcnt(7)
	ds_write_b128 v173, v[52:55] offset:16384
	s_waitcnt vmcnt(6)
	ds_write_b128 v174, v[56:59] offset:16384
	s_waitcnt vmcnt(5)
	ds_write_b128 v171, v[60:63] offset:49152
	s_waitcnt vmcnt(4)
	ds_write_b128 v172, v[64:67] offset:49152
	v_sub_f32_e32 v52, 0xf149f2ca, v51
	v_mul_f32_e32 v52, 0x3e38aa3b, v52
	v_exp_f32_e32 v52, v52
	s_cmp_eq_u64 vcc, exec
	s_cselect_b64 vcc, -1, 0
	v_cndmask_b32_e32 v148, v51, v222, vcc
	v_cndmask_b32_e64 v188, v52, 1.0, vcc
	v_mul_f32_e32 v52, 0xbe38aa3b, v148
	v_fmamk_f32 v16, v16, 0x3e38aa3b, v52
	v_exp_f32_e32 v145, v16
	v_fmamk_f32 v16, v17, 0x3e38aa3b, v52
	v_exp_f32_e32 v158, v16
	v_fmamk_f32 v16, v18, 0x3e38aa3b, v52
	v_exp_f32_e32 v146, v16
	v_fmamk_f32 v16, v19, 0x3e38aa3b, v52
	v_exp_f32_e32 v159, v16
	v_fmamk_f32 v16, v20, 0x3e38aa3b, v52
	v_exp_f32_e32 v147, v16
	v_fmamk_f32 v16, v21, 0x3e38aa3b, v52
	v_exp_f32_e32 v200, v16
	v_fmamk_f32 v16, v22, 0x3e38aa3b, v52
	v_exp_f32_e32 v157, v16
	v_fmamk_f32 v16, v23, 0x3e38aa3b, v52
	v_exp_f32_e32 v203, v16
	v_fmamk_f32 v16, v24, 0x3e38aa3b, v52
	v_exp_f32_e32 v149, v16
	v_fmamk_f32 v16, v25, 0x3e38aa3b, v52
	v_exp_f32_e32 v153, v16
	v_fmamk_f32 v16, v26, 0x3e38aa3b, v52
	v_exp_f32_e32 v150, v16
	v_fmamk_f32 v16, v27, 0x3e38aa3b, v52
	v_exp_f32_e32 v154, v16
	v_fmamk_f32 v16, v28, 0x3e38aa3b, v52
	v_exp_f32_e32 v151, v16
	v_fmamk_f32 v16, v29, 0x3e38aa3b, v52
	s_addk_i32 s36, 0x4000
	s_and_b32 s0, s29, 3
	v_exp_f32_e32 v155, v16
	v_fmamk_f32 v16, v30, 0x3e38aa3b, v52
	v_add_u32_e32 v168, s36, v77
	s_lshl_b32 s36, s0, 8
	v_pk_fma_f32 v[128:129], v[46:47], s[68:69], v[52:53] op_sel_hi:[1,0,0]
	v_pk_fma_f32 v[134:135], v[44:45], s[68:69], v[52:53] op_sel_hi:[1,0,0]
	v_pk_fma_f32 v[138:139], v[42:43], s[68:69], v[52:53] op_sel_hi:[1,0,0]
	v_pk_fma_f32 v[130:131], v[40:41], s[68:69], v[52:53] op_sel_hi:[1,0,0]
	v_pk_fma_f32 v[132:133], v[38:39], s[68:69], v[52:53] op_sel_hi:[1,0,0]
	v_pk_fma_f32 v[136:137], v[36:37], s[68:69], v[52:53] op_sel_hi:[1,0,0]
	v_pk_fma_f32 v[140:141], v[34:35], s[68:69], v[52:53] op_sel_hi:[1,0,0]
	v_pk_fma_f32 v[142:143], v[32:33], s[68:69], v[52:53] op_sel_hi:[1,0,0]
	v_exp_f32_e32 v152, v16
	v_fmac_f32_e32 v52, 0x3e38aa3b, v31
	v_lshl_add_u64 v[16:17], s[22:23], 0, v[48:49]
	v_mov_b64_e32 v[18:19], s[36:37]
	v_exp_f32_e32 v156, v52
	v_mad_u64_u32 v[18:19], s[0:1], v16, s28, v[18:19]
	v_and_b32_e32 v16, 15, v50
	v_mad_i32_i24 v17, v17, s28, v19
	v_lshl_or_b32 v16, v16, 4, v18
	v_lshl_add_u64 v[162:163], s[12:13], 0, v[16:17]
	v_mov_b64_e32 v[62:63], v[14:15]
	v_mov_b64_e32 v[46:47], v[14:15]
	v_mov_b64_e32 v[30:31], v[14:15]
	v_cmp_gt_u32_e64 s[6:7], 32, v76
	s_add_i32 s89, s89, -3
	v_mov_b64_e32 v[60:61], v[12:13]
	v_mov_b64_e32 v[58:59], v[10:11]
	v_mov_b64_e32 v[56:57], v[8:9]
	v_mov_b64_e32 v[54:55], v[6:7]
	v_mov_b64_e32 v[52:53], v[4:5]
	v_mov_b64_e32 v[50:51], v[2:3]
	v_mov_b64_e32 v[48:49], v[0:1]
	v_mov_b64_e32 v[44:45], v[12:13]
	v_mov_b64_e32 v[42:43], v[10:11]
	v_mov_b64_e32 v[40:41], v[8:9]
	v_mov_b64_e32 v[38:39], v[6:7]
	v_mov_b64_e32 v[36:37], v[4:5]
	v_mov_b64_e32 v[34:35], v[2:3]
	v_mov_b64_e32 v[32:33], v[0:1]
	v_mov_b64_e32 v[28:29], v[12:13]
	v_mov_b64_e32 v[26:27], v[10:11]
	v_mov_b64_e32 v[24:25], v[8:9]
	v_mov_b64_e32 v[22:23], v[6:7]
	v_mov_b64_e32 v[20:21], v[4:5]
	v_mov_b64_e32 v[18:19], v[2:3]
	v_mov_b64_e32 v[16:17], v[0:1]
	s_waitcnt lgkmcnt(0)
	s_barrier

.LBB0_706:
	v_ashrrev_i32_e32 v48, 4, v50
	v_lshlrev_b32_e32 v16, 3, v50
	v_add_u32_e32 v17, 32, v48
	s_movk_i32 s6, 0x300
	v_and_b32_e32 v51, 0x78, v16
	s_waitcnt vmcnt(3)
	v_mad_i64_i32 v[0:1], s[0:1], v48, s6, 0
	v_mad_i64_i32 v[2:3], s[0:1], v17, s6, 0
	v_or_b32_e32 v0, v0, v51
	v_or_b32_e32 v2, v2, v51
	s_waitcnt vmcnt(1)
	v_lshlrev_b64 v[8:9], 1, v[0:1]
	v_lshlrev_b64 v[10:11], 1, v[2:3]
	v_lshl_add_u64 v[0:1], s[26:27], 0, v[8:9]
	v_lshl_add_u64 v[4:5], s[26:27], 0, v[10:11]
	v_lshl_add_u64 v[8:9], s[24:25], 0, v[8:9]
	s_waitcnt vmcnt(0)
	v_lshl_add_u64 v[12:13], s[24:25], 0, v[10:11]
	global_load_dwordx4 v[0:3], v[0:1], off offset:512
	s_nop 0
	global_load_dwordx4 v[4:7], v[4:5], off offset:512
	s_nop 0
	global_load_dwordx4 v[8:11], v[8:9], off offset:512
	s_nop 0
	global_load_dwordx4 v[12:15], v[12:13], off offset:512
	v_lshlrev_b32_e32 v21, 4, v165
	v_and_b32_e32 v23, 0xfffff0, v48
	v_lshlrev_b32_e32 v24, 1, v48
	v_lshrrev_b32_e32 v25, 1, v48
	v_and_b32_e32 v26, 3, v48
	v_or_b32_e32 v20, 0x80, v178
	v_lshlrev_b32_e32 v68, 8, v165
	v_and_b32_e32 v69, 0xf0, v21
	v_and_or_b32 v21, v24, 8, v23
	v_and_or_b32 v23, v25, 4, v26
	v_and_b32_e32 v25, 0xfffff0, v17
	v_lshlrev_b32_e32 v26, 1, v17
	v_and_b32_e32 v19, 0xf0, v50
	v_bfe_u32 v16, v16, 5, 2
	v_lshlrev_b32_e32 v27, 8, v48
	v_lshlrev_b32_e32 v24, 1, v51
	v_lshlrev_b32_e32 v17, 8, v17
	v_bitop3_b32 v20, v20, v68, v69 bitop3:0xde
	v_lshrrev_b32_e32 v21, 1, v21
	v_and_or_b32 v25, v26, 8, v25
	v_bitop3_b32 v26, v24, v27, v19 bitop3:0xde
	v_bitop3_b32 v17, v24, v17, v19 bitop3:0xde
	v_add_u32_e32 v170, 0x100, v20
	v_or_b32_e32 v19, v21, v16
	v_lshrrev_b32_e32 v20, 1, v25
	v_lshlrev_b32_e32 v23, 6, v23
	v_and_b32_e32 v28, 48, v24
	v_add_u32_e32 v172, 0x100, v17
	v_lshlrev_b32_e32 v17, 9, v19
	v_or_b32_e32 v16, v20, v16
	v_or3_b32 v17, v17, v23, v28
	v_lshlrev_b32_e32 v16, 9, v16
	v_or3_b32 v16, v16, v23, v28
	v_add_u32_e32 v173, 0x100, v17
	v_add_u32_e32 v171, 0x100, v26
	s_waitcnt vmcnt(0)
	v_add_u32_e32 v174, 0x100, v16
	v_and_b32_e32 v76, 63, v50
	v_or_b32_e32 v22, 0xa0, v178
	v_lshlrev_b32_e32 v21, 4, v76
	v_and_b32_e32 v39, 0xc0, v21
	v_bitop3_b32 v21, v22, v68, v69 bitop3:0xde
	v_add_u32_e32 v186, 0x100, v21
	v_and_b32_e32 v18, 0x3fffffc0, v50
	v_lshl_add_u32 v161, v18, 2, s90
	v_or_b32_e32 v20, 0xc0, v178
	v_bitop3_b32 v44, v20, v68, v69 bitop3:0xde
	v_lshlrev_b32_e32 v36, 3, v76
	v_add_u32_e32 v37, 64, v48
	v_add_u32_e32 v38, 0x60, v48
	v_add_u32_e32 v175, 0x100, v44
	v_and_b32_e32 v70, 0x100, v36
	v_mad_i64_i32 v[40:41], s[0:1], v37, s6, 0
	v_mad_i64_i32 v[42:43], s[0:1], v38, s6, 0
	v_and_or_b32 v71, v36, 24, v39
	v_lshlrev_b32_e32 v23, 1, v76
	v_and_b32_e32 v49, 32, v23
	v_or_b32_e32 v40, v40, v51
	v_or_b32_e32 v42, v42, v51
	v_lshlrev_b64 v[40:41], 1, v[40:41]
	v_lshlrev_b64 v[42:43], 1, v[42:43]
	v_lshl_add_u64 v[44:45], s[26:27], 0, v[40:41]
	v_lshl_add_u64 v[46:47], s[26:27], 0, v[42:43]
	v_or3_b32 v77, v71, v49, v70
	v_add_u32_e32 v72, 0xa0, v48
	s_waitcnt vmcnt(3)
	ds_write_b128 v173, v[0:3]
	s_waitcnt vmcnt(2)
	ds_write_b128 v174, v[4:7]
	s_waitcnt vmcnt(1)
	ds_write_b128 v171, v[8:11] offset:32768
	s_waitcnt vmcnt(0)
	ds_write_b128 v172, v[12:15] offset:32768
	s_waitcnt lgkmcnt(0)
	s_barrier
	ds_read_b128 v[0:3], v170 offset:32768
	ds_read_b128 v[16:19], v170 offset:40960
	ds_read_b128 v[32:35], v186 offset:32768
	s_waitcnt lgkmcnt(2)
	v_mfma_f32_32x32x16_bf16 v[0:15], v[0:3], v[100:103], 0
	ds_read_b128 v[36:39], v186 offset:40960
	v_mad_i64_i32 v[72:73], s[0:1], v72, s6, 0
	v_or_b32_e32 v72, v72, v51
	v_lshlrev_b64 v[72:73], 1, v[72:73]
	v_lshl_add_u64 v[74:75], s[26:27], 0, v[72:73]
	s_lshl_b64 s[18:19], s[20:21], 11
	s_waitcnt lgkmcnt(1)
	v_mfma_f32_32x32x16_bf16 v[0:15], v[32:35], v[108:111], v[0:15]
	ds_read_b128 v[32:35], v175 offset:32768
	global_load_dwordx4 v[52:55], v[44:45], off offset:512
	global_load_dwordx4 v[56:59], v[46:47], off offset:512
	s_cmp_lg_u32 0x100, -1
	s_cselect_b32 s20, 0x100, 0
	v_ashrrev_i32_e32 v49, 31, v48
	s_movk_i32 s90, 0x600
	s_mov_b32 s49, s48
	v_mfma_f32_32x32x16_bf16 v[16:31], v[16:19], v[100:103], 0
	s_mov_b32 s50, s48
	s_mov_b32 s51, s48
	s_mov_b32 s52, s48
	s_mov_b32 s53, s48
	s_mov_b32 s54, s48
	s_mov_b32 s55, s48
	s_mov_b32 s56, s48
	s_waitcnt lgkmcnt(0)
	v_mfma_f32_32x32x16_bf16 v[0:15], v[32:35], v[96:99], v[0:15]
	v_or_b32_e32 v32, 0xe0, v178
	v_bitop3_b32 v32, v32, v68, v69 bitop3:0xde
	v_add_u32_e32 v187, 0x100, v32
	s_mov_b32 s57, s48
	s_mov_b32 s58, s48
	s_mov_b32 s59, s48
	s_mov_b32 s60, s48
	v_mfma_f32_32x32x16_bf16 v[16:31], v[36:39], v[108:111], v[16:31]
	v_lshl_add_u64 v[36:37], s[24:25], 0, v[40:41]
	v_lshl_add_u64 v[38:39], s[24:25], 0, v[42:43]
	global_load_dwordx4 v[60:63], v[36:37], off offset:512
	global_load_dwordx4 v[64:67], v[38:39], off offset:512
	ds_read_b128 v[36:39], v175 offset:40960
	ds_read_b128 v[32:35], v187 offset:32768
	ds_read_b128 v[68:71], v187 offset:40960
	s_mov_b32 s61, s48
	s_waitcnt lgkmcnt(2)
	v_mfma_f32_32x32x16_bf16 v[16:31], v[36:39], v[96:99], v[16:31]
	s_mov_b32 s62, s48
	s_mov_b32 s63, s48
	v_add_u32_e32 v169, s20, v77
	s_mov_b32 s30, 1
	v_lshl_add_u32 v166, v165, 2, v161
	v_mov_b32_e32 v167, 0
	s_waitcnt lgkmcnt(1)
	v_mfma_f32_32x32x16_bf16 v[0:15], v[32:35], v[104:107], v[0:15]
	v_mov_b64_e32 v[32:33], s[48:49]
	v_mov_b64_e32 v[46:47], s[62:63]
	v_mov_b64_e32 v[34:35], s[50:51]
	v_mov_b64_e32 v[36:37], s[52:53]
	v_mov_b64_e32 v[38:39], s[54:55]
	v_mov_b64_e32 v[40:41], s[56:57]
	v_mov_b64_e32 v[42:43], s[58:59]
	s_waitcnt lgkmcnt(0)
	v_mfma_f32_32x32x16_bf16 v[16:31], v[68:71], v[104:107], v[16:31]
	s_nop 2
	v_max_f32_e32 v68, v1, v1
	v_max_f32_e32 v69, v0, v0
	v_max_f32_e32 v68, v69, v68
	v_max3_f32 v68, v68, v2, v3
	v_max3_f32 v68, v68, v4, v5
	v_max3_f32 v68, v68, v6, v7
	v_max3_f32 v68, v68, v8, v9
	v_max3_f32 v68, v68, v10, v11
	v_max3_f32 v68, v68, v12, v13
	v_max3_f32 v68, v68, v14, v15
	v_max3_f32 v68, v68, v16, v17
	v_max3_f32 v68, v68, v18, v19
	v_max3_f32 v68, v68, v20, v21
	v_max3_f32 v68, v68, v22, v23
	v_max3_f32 v68, v68, v24, v25
	v_max3_f32 v68, v68, v26, v27
	v_max3_f32 v68, v68, v28, v29
	v_max3_f32 v78, v68, v30, v31
	v_mov_b32_e32 v68, v78
	s_nop 1
	v_permlane32_swap_b32_e32 v78, v68
	v_max_f32_e32 v79, v68, v68
	v_add_u32_e32 v68, 0x80, v48
	v_mad_i64_i32 v[68:69], s[0:1], v68, s6, 0
	v_or_b32_e32 v68, v68, v51
	v_lshlrev_b64 v[68:69], 1, v[68:69]
	v_lshl_add_u64 v[70:71], s[26:27], 0, v[68:69]
	v_lshl_add_u64 v[68:69], s[24:25], 0, v[68:69]
	global_load_dwordx4 v[112:115], v[70:71], off offset:512
	global_load_dwordx4 v[120:123], v[74:75], off offset:512
	v_lshl_add_u64 v[70:71], s[24:25], 0, v[72:73]
	global_load_dwordx4 v[116:119], v[68:69], off offset:512
	global_load_dwordx4 v[124:127], v[70:71], off offset:512
	v_max_f32_e32 v51, v78, v78
	v_max_f32_e32 v51, v51, v79
	v_add_f32_e32 v68, 0x7149f2ca, v51
	v_max_f32_e32 v51, 0xf149f2ca, v51
	s_waitcnt vmcnt(4)
	s_waitcnt vmcnt(7)
	ds_write_b128 v173, v[52:55] offset:16384
	s_waitcnt vmcnt(6)
	ds_write_b128 v174, v[56:59] offset:16384
	s_waitcnt vmcnt(5)
	ds_write_b128 v171, v[60:63] offset:49152
	s_waitcnt vmcnt(4)
	ds_write_b128 v172, v[64:67] offset:49152
	v_sub_f32_e32 v52, 0xf149f2ca, v51
	s_mov_b32 s26, 0x42800000
	v_mul_f32_e32 v52, 0x3e38aa3b, v52
	v_cmp_ge_f32_e32 vcc, s26, v68
	v_exp_f32_e32 v52, v52
	s_cmp_eq_u64 vcc, exec
	s_cselect_b64 vcc, -1, 0
	v_cndmask_b32_e32 v148, v51, v222, vcc
	v_cndmask_b32_e64 v188, v52, 1.0, vcc
	v_mul_f32_e32 v52, 0xbe38aa3b, v148
	v_fmamk_f32 v0, v0, 0x3e38aa3b, v52
	v_exp_f32_e32 v145, v0
	v_fmamk_f32 v0, v1, 0x3e38aa3b, v52
	v_exp_f32_e32 v158, v0
	v_fmamk_f32 v0, v2, 0x3e38aa3b, v52
	v_exp_f32_e32 v146, v0
	v_fmamk_f32 v0, v3, 0x3e38aa3b, v52
	v_exp_f32_e32 v159, v0
	v_fmamk_f32 v0, v4, 0x3e38aa3b, v52
	v_exp_f32_e32 v147, v0
	v_fmamk_f32 v0, v5, 0x3e38aa3b, v52
	v_exp_f32_e32 v200, v0
	v_fmamk_f32 v0, v6, 0x3e38aa3b, v52
	v_exp_f32_e32 v157, v0
	v_fmamk_f32 v0, v7, 0x3e38aa3b, v52
	v_exp_f32_e32 v203, v0
	v_fmamk_f32 v0, v8, 0x3e38aa3b, v52
	v_exp_f32_e32 v149, v0
	v_fmamk_f32 v0, v9, 0x3e38aa3b, v52
	v_exp_f32_e32 v153, v0
	v_fmamk_f32 v0, v10, 0x3e38aa3b, v52
	v_exp_f32_e32 v150, v0
	v_fmamk_f32 v0, v11, 0x3e38aa3b, v52
	v_exp_f32_e32 v154, v0
	v_fmamk_f32 v0, v12, 0x3e38aa3b, v52
	v_exp_f32_e32 v151, v0
	v_fmamk_f32 v0, v13, 0x3e38aa3b, v52
	v_exp_f32_e32 v155, v0
	v_fmamk_f32 v0, v14, 0x3e38aa3b, v52
	v_exp_f32_e32 v152, v0
	v_lshl_add_u64 v[0:1], s[22:23], 0, v[48:49]
	v_mov_b64_e32 v[2:3], s[36:37]
	v_pk_fma_f32 v[128:129], v[30:31], s[68:69], v[52:53] op_sel_hi:[1,0,0]
	v_pk_fma_f32 v[134:135], v[28:29], s[68:69], v[52:53] op_sel_hi:[1,0,0]
	v_pk_fma_f32 v[138:139], v[26:27], s[68:69], v[52:53] op_sel_hi:[1,0,0]
	v_pk_fma_f32 v[130:131], v[24:25], s[68:69], v[52:53] op_sel_hi:[1,0,0]
	v_pk_fma_f32 v[132:133], v[22:23], s[68:69], v[52:53] op_sel_hi:[1,0,0]
	v_pk_fma_f32 v[136:137], v[20:21], s[68:69], v[52:53] op_sel_hi:[1,0,0]
	v_pk_fma_f32 v[140:141], v[18:19], s[68:69], v[52:53] op_sel_hi:[1,0,0]
	v_pk_fma_f32 v[142:143], v[16:17], s[68:69], v[52:53] op_sel_hi:[1,0,0]
	v_fmac_f32_e32 v52, 0x3e38aa3b, v15
	v_mad_u64_u32 v[2:3], s[0:1], v0, s90, v[2:3]
	v_and_b32_e32 v0, 15, v50
	v_exp_f32_e32 v156, v52
	v_mad_i32_i24 v3, v1, s90, v3
	v_lshlrev_b32_e32 v0, 4, v0
	v_mov_b32_e32 v1, v179
	v_lshl_add_u64 v[0:1], v[2:3], 0, v[0:1]
	v_mov_b64_e32 v[44:45], s[60:61]
	s_addk_i32 s20, 0x4000
	v_lshl_add_u64 v[162:163], s[12:13], 0, v[0:1]
	v_mov_b64_e32 v[62:63], v[46:47]
	v_mov_b64_e32 v[16:17], v[32:33]
	v_mov_b64_e32 v[0:1], v[32:33]
	v_cmp_gt_u32_e64 s[6:7], 32, v76
	v_add_u32_e32 v168, s20, v77
	v_mov_b64_e32 v[60:61], v[44:45]
	v_mov_b64_e32 v[58:59], v[42:43]
	v_mov_b64_e32 v[56:57], v[40:41]
	v_mov_b64_e32 v[54:55], v[38:39]
	v_mov_b64_e32 v[52:53], v[36:37]
	v_mov_b64_e32 v[50:51], v[34:35]
	v_mov_b64_e32 v[48:49], v[32:33]
	v_mov_b64_e32 v[18:19], v[34:35]
	v_mov_b64_e32 v[20:21], v[36:37]
	v_mov_b64_e32 v[22:23], v[38:39]
	v_mov_b64_e32 v[24:25], v[40:41]
	v_mov_b64_e32 v[26:27], v[42:43]
	v_mov_b64_e32 v[28:29], v[44:45]
	v_mov_b64_e32 v[30:31], v[46:47]
	v_mov_b64_e32 v[2:3], v[34:35]
	v_mov_b64_e32 v[4:5], v[36:37]
	v_mov_b64_e32 v[6:7], v[38:39]
	v_mov_b64_e32 v[8:9], v[40:41]
	v_mov_b64_e32 v[10:11], v[42:43]
	v_mov_b64_e32 v[12:13], v[44:45]
	v_mov_b64_e32 v[14:15], v[46:47]
	s_waitcnt lgkmcnt(0)
	s_barrier
